# ret_scan: next chunk's K^T/V^T loads issued at the top of the iteration into own registers (vmcnt order K,V | Q | stores)
# speedup vs baseline: 1.0279x; 1.0119x over previous
.LBB0_638:
	s_or_b64 exec, exec, s[10:11]
	s_and_b32 s0, s51, 56
	s_ashr_i32 s16, s4, 3
	s_or_b32 s1, s0, s16
	s_ashr_i32 s4, s1, 3
	s_and_b32 s17, s4, 3
	v_cvt_f32_ubyte0_e32 v1, s17
	v_sub_f32_e32 v1, 0xc0a00000, v1
	s_mov_b32 s0, 0xc2fc0000
	v_mov_b32_e32 v14, 0x42800000
	v_cmp_gt_f32_e32 vcc, s0, v1
	s_lshl_b32 s13, s16, 5
	s_and_b64 s[8:9], vcc, exec
	v_cndmask_b32_e32 v2, 0, v14, vcc
	v_add_f32_e32 v1, v1, v2
	v_exp_f32_e32 v1, v1
	s_cselect_b32 s5, 0xffffffc0, 0
	v_mov_b32_e32 v2, 0x42000000
	v_mov_b32_e32 v3, 0
	v_ldexp_f32 v1, v1, s5
	v_sub_f32_e32 v1, 1.0, v1
	s_mov_b32 s5, 0x800000
	v_cmp_gt_f32_e32 vcc, s5, v1
	s_and_b64 s[8:9], vcc, exec
	s_cselect_b32 s5, 32, 0
	v_ldexp_f32 v1, v1, s5
	v_log_f32_e32 v1, v1
	v_cndmask_b32_e32 v2, 0, v2, vcc
	v_and_b32_e32 v6, 0x3f00, v131
	v_mov_b32_e32 v7, v3
	v_sub_f32_e32 v1, v1, v2
	v_mul_f32_e32 v2, 0x43000000, v1
	v_cmp_gt_f32_e32 vcc, s0, v2
	s_and_b64 s[10:11], vcc, exec
	s_cselect_b32 s5, 0xffffffc0, 0
	v_cndmask_b32_e32 v2, 0, v14, vcc
	v_fmac_f32_e32 v2, 0x43000000, v1
	v_exp_f32_e32 v2, v2
	s_ashr_i32 s12, s1, 5
	s_and_b32 s14, s13, 0xe0
	s_movk_i32 s1, 0x2000
	v_ldexp_f32 v122, v2, s5
	s_ashr_i32 s5, s4, 31
	s_lshl_b64 s[10:11], s[4:5], 23
	s_add_u32 s18, s78, s10
	s_addc_u32 s19, s79, s11
	v_and_b32_e32 v2, 0xf0, v131
	v_lshl_add_u64 v[4:5], s[18:19], 0, v[2:3]
	s_mov_b64 s[4:5], 0x38000000
	v_lshl_add_u64 v[4:5], v[4:5], 0, s[4:5]
	v_lshl_add_u64 v[8:9], v[4:5], 0, v[6:7]
	v_add_co_u32_e32 v10, vcc, s1, v8
	s_movk_i32 s1, 0x6000
	s_nop 0
	v_addc_co_u32_e32 v11, vcc, 0, v9, vcc
	global_load_dwordx4 v[200:203], v[8:9], off
	global_load_dwordx4 v[204:207], v[10:11], off
	v_or_b32_e32 v10, 0x4000, v6
	v_mov_b32_e32 v11, v3
	v_add_co_u32_e32 v12, vcc, s1, v8
	v_lshl_add_u64 v[10:11], v[4:5], 0, v[10:11]
	s_nop 0
	v_addc_co_u32_e32 v13, vcc, 0, v9, vcc
	s_mov_b32 s1, 0xa000
	global_load_dwordx4 v[208:211], v[10:11], off
	global_load_dwordx4 v[212:215], v[12:13], off
	v_add_co_u32_e32 v12, vcc, s1, v8
	v_or_b32_e32 v10, 0x8000, v6
	v_mov_b32_e32 v11, v3
	v_addc_co_u32_e32 v13, vcc, 0, v9, vcc
	v_or_b32_e32 v6, 0xc000, v6
	s_mov_b32 s1, 0xe000
	v_lshl_add_u64 v[10:11], v[4:5], 0, v[10:11]
	v_lshl_add_u64 v[4:5], v[4:5], 0, v[6:7]
	v_add_co_u32_e32 v6, vcc, s1, v8
	v_lshrrev_b32_e32 v16, 4, v153
	global_load_dwordx4 v[216:219], v[10:11], off
	global_load_dwordx4 v[220:223], v[12:13], off
	v_addc_co_u32_e32 v7, vcc, 0, v9, vcc
	global_load_dwordx4 v[224:227], v[4:5], off
	global_load_dwordx4 v[228:231], v[6:7], off
	v_add_lshl_u32 v4, s14, v16, 8
	v_mov_b32_e32 v5, v3
	v_lshl_add_u64 v[6:7], s[18:19], 0, v[4:5]
	s_ashr_i32 s13, s12, 31
	v_lshl_add_u64 v[6:7], v[6:7], 0, v[2:3]
	s_brev_b32 s1, 60
	s_lshl_b64 s[4:5], s[12:13], 14
	v_add_co_u32_e32 v6, vcc, s1, v6
	s_lshl_b32 s1, s50, 4
	s_add_u32 s8, s4, s1
	s_addc_u32 s15, s5, 0
	v_or_b32_e32 v8, s8, v130
	v_mov_b32_e32 v9, s15
	v_lshlrev_b64 v[8:9], 13, v[8:9]
	s_mov_b32 s9, 0
	v_lshl_add_u64 v[10:11], s[6:7], 0, v[8:9]
	s_lshl_b32 s8, s17, 9
	v_addc_co_u32_e32 v7, vcc, 0, v7, vcc
	v_lshl_add_u64 v[10:11], v[10:11], 0, s[8:9]
	v_and_b32_e32 v12, 48, v152
	v_mov_b32_e32 v13, v3
	v_lshl_add_u64 v[10:11], v[10:11], 0, v[12:13]
	global_load_dwordx4 v[232:235], v[6:7], off
	global_load_dwordx4 v[90:93], v[10:11], off
	global_load_dwordx4 v[86:89], v[10:11], off offset:64
	global_load_dwordx4 v[82:85], v[10:11], off offset:128
	global_load_dwordx4 v[78:81], v[10:11], off offset:192
	global_load_dwordx4 v[62:65], v[10:11], off offset:256
	global_load_dwordx4 v[46:49], v[10:11], off offset:320
	global_load_dwordx4 v[30:33], v[10:11], off offset:384
	global_load_dwordx4 v[22:25], v[10:11], off offset:448
	v_lshrrev_b32_e32 v15, 4, v152
	v_lshl_or_b32 v134, v15, 2, s1
	v_or_b32_e32 v132, 1, v134
	v_cvt_f32_u32_e32 v7, v132
	v_or_b32_e32 v128, 2, v134
	v_not_b32_e32 v42, 63
	v_or_b32_e32 v124, 3, v134
	v_mul_f32_e32 v17, v1, v7
	v_cmp_gt_f32_e32 vcc, s0, v17
	v_and_b32_e32 v5, 48, v153
	s_add_i32 s6, 0, 0x13200
	v_cndmask_b32_e32 v17, 0, v14, vcc
	v_fmac_f32_e32 v17, v1, v7
	v_cvt_f32_u32_e32 v7, v128
	v_cndmask_b32_e32 v43, 0, v42, vcc
	v_exp_f32_e32 v17, v17
	s_and_b32 s1, s3, 0xffffffc0
	v_mul_f32_e32 v44, v1, v7
	v_cmp_gt_f32_e32 vcc, s0, v44
	v_ldexp_f32 v148, v17, v43
	v_add_u32_e32 v10, s6, v5
	v_cndmask_b32_e32 v44, 0, v14, vcc
	v_fmac_f32_e32 v44, v1, v7
	v_exp_f32_e32 v7, v44
	v_cndmask_b32_e32 v17, 0, v42, vcc
	v_cvt_f32_u32_e32 v44, v124
	s_add_i32 s6, s6, s1
	v_ldexp_f32 v145, v7, v17
	v_add_u32_e32 v17, 4, v134
	v_cvt_f32_u32_e32 v17, v17
	v_mul_f32_e32 v7, v1, v44
	v_cmp_gt_f32_e32 vcc, s0, v7
	v_lshl_or_b32 v6, s50, 5, v130
	v_mul_f32_e32 v43, v1, v17
	v_cndmask_b32_e32 v7, 0, v14, vcc
	v_cmp_gt_f32_e64 s[0:1], s0, v43
	v_fmac_f32_e32 v7, v1, v44
	v_exp_f32_e32 v7, v7
	v_cndmask_b32_e64 v14, 0, v14, s[0:1]
	v_fmac_f32_e32 v14, v1, v17
	v_exp_f32_e32 v1, v14
	v_cndmask_b32_e32 v14, 0, v42, vcc
	v_ldexp_f32 v144, v7, v14
	v_cndmask_b32_e64 v7, 0, v42, s[0:1]
	v_ldexp_f32 v1, v1, v7
	v_add_u32_e32 v7, 0x200, v153
	v_lshrrev_b32_e32 v7, 4, v7
	v_mul_u32_u24_e32 v7, 0x110, v7
	v_add3_u32 v133, 0, v7, v2
	v_add_u32_e32 v7, 0x600, v153
	v_lshrrev_b32_e32 v7, 4, v7
	v_mul_u32_u24_e32 v7, 0x110, v7
	v_add3_u32 v149, 0, v7, v2
	v_add_u32_e32 v7, 0xa00, v153
	v_lshrrev_b32_e32 v7, 4, v7
	v_mul_u32_u24_e32 v7, 0x110, v7
	v_add3_u32 v150, 0, v7, v2
	v_add_u32_e32 v7, 0xe00, v153
	s_movk_i32 s0, 0x110
	v_lshrrev_b32_e32 v7, 4, v7
	s_add_i32 s7, 0, 0x11000
	v_mul_lo_u32 v14, v6, s0
	v_mul_u32_u24_e32 v6, 0x110, v16
	v_mul_u32_u24_e32 v7, 0x110, v7
	v_mov_b32_e32 v135, v3
	v_add3_u32 v125, 0, v6, v2
	v_add3_u32 v151, 0, v7, v2
	v_add3_u32 v154, s7, v6, v2
	s_lshl_b64 s[0:1], s[12:13], 26
	v_lshlrev_b64 v[6:7], 12, v[134:135]
	v_lshl_add_u64 v[136:137], s[0:1], 0, v[6:7]
	s_lshl_b32 s0, s16, 6
	v_or_b32_e32 v2, s8, v136
	s_and_b32 s0, s0, 0x1c0
	v_lshlrev_b32_e32 v6, 1, v130
	v_or3_b32 v136, v2, s0, v6
	v_lshl_or_b32 v2, v130, 4, s10
	v_or_b32_e32 v138, v2, v4
	v_mov_b32_e32 v139, s11
	s_mov_b64 s[0:1], 0x3c010000
	v_add_u32_e32 v11, 0, v5
	v_add_u32_e32 v12, s7, v5
	v_lshl_add_u32 v13, v15, 3, s6
	v_mul_u32_u24_e32 v15, 0x210, v130
	v_mul_u32_u24_e32 v17, 0x110, v130
	v_lshl_add_u64 v[140:141], v[138:139], 0, s[0:1]
	v_or3_b32 v8, v8, s8, v5
	s_mov_b64 s[0:1], 0x1c100100
	s_lshl_b32 s15, s17, 8
	v_mov_b32_e32 v126, v122
	v_mov_b32_e32 v127, v122
	v_lshl_or_b32 v138, v16, 8, v2
	v_lshl_add_u64 v[142:143], v[8:9], 0, s[0:1]
	s_movk_i32 s10, 0x7f
	s_mov_b32 s11, 0x38010000
	s_mov_b32 s12, 0x38012000
	s_mov_b32 s13, 0x38014000
	s_mov_b32 s16, 0x38016000
	s_mov_b32 s17, 0x38018000
	s_mov_b32 s18, 0x3801a000
	s_mov_b32 s19, 0x3801c000
	s_mov_b32 s20, 0x3801e000
	s_movk_i32 s21, 0x7fff
	s_mov_b32 s22, 0xf000000
	s_mov_b32 s23, 0xf001000
	s_mov_b32 s24, 0xf002000
	s_mov_b32 s25, 0xf003000
	s_mov_b32 s26, 0xffff0000
	s_mov_b64 s[0:1], 0x80000
	s_mov_b64 s[6:7], 0x10000
	s_mov_b64 s[8:9], 0x100000
	v_add_u32_e32 v129, v10, v15
	v_add_u32_e32 v146, v11, v14
	v_add_u32_e32 v147, v12, v17
	v_add_u32_e32 v131, v13, v15
	v_mov_b32_e32 v2, v3
	v_mov_b32_e32 v4, v3
	v_mov_b32_e32 v5, v3
	v_mov_b32_e32 v6, v3
	v_mov_b32_e32 v7, v3
	v_mov_b32_e32 v8, v3
	v_mov_b32_e32 v9, v3
	v_mov_b32_e32 v10, v3
	v_mov_b32_e32 v11, v3
	v_mov_b32_e32 v12, v3
	v_mov_b32_e32 v13, v3
	v_mov_b32_e32 v14, v3
	v_mov_b32_e32 v15, v3
	v_mov_b32_e32 v16, v3
	v_mov_b32_e32 v17, v3
	v_lshl_add_u64 v[34:35], s[78:79], 0, v[138:139]
	v_add_co_u32_e32 v240, vcc, s11, v34
	s_nop 1
	v_addc_co_u32_e32 v241, vcc, 0, v35, vcc
	v_add_co_u32_e32 v242, vcc, s12, v34
	s_nop 1
	v_addc_co_u32_e32 v243, vcc, 0, v35, vcc
	v_add_co_u32_e32 v244, vcc, s13, v34
	s_nop 1
	v_addc_co_u32_e32 v245, vcc, 0, v35, vcc
	v_add_co_u32_e32 v246, vcc, s16, v34
	s_nop 1
	v_addc_co_u32_e32 v247, vcc, 0, v35, vcc
	v_add_co_u32_e32 v248, vcc, s17, v34
	s_nop 1
	v_addc_co_u32_e32 v249, vcc, 0, v35, vcc
	v_add_co_u32_e32 v250, vcc, s18, v34
	s_nop 1
	v_addc_co_u32_e32 v251, vcc, 0, v35, vcc
	v_add_co_u32_e32 v252, vcc, s19, v34
	s_nop 1
	v_addc_co_u32_e32 v253, vcc, 0, v35, vcc
	v_add_co_u32_e32 v254, vcc, s20, v34
	s_nop 1
	v_addc_co_u32_e32 v255, vcc, 0, v35, vcc
	v_lshl_add_u64 v[236:237], s[78:79], 0, v[140:141]
	s_waitcnt vmcnt(0)
.LBB0_639:
	s_waitcnt vmcnt(16)
	ds_write_b128 v125, v[200:203]
	ds_write_b128 v133, v[204:207]
	ds_write_b128 v125, v[208:211] offset:17408
	ds_write_b128 v149, v[212:215]
	ds_write_b128 v125, v[216:219] offset:34816
	ds_write_b128 v150, v[220:223]
	ds_write_b128 v125, v[224:227] offset:52224
	ds_write_b128 v151, v[228:231]
	ds_write_b128 v154, v[232:235]
	s_waitcnt lgkmcnt(0)
	global_load_dwordx4 v[200:203], v[240:241], off
	global_load_dwordx4 v[204:207], v[242:243], off
	global_load_dwordx4 v[208:211], v[244:245], off
	global_load_dwordx4 v[212:215], v[246:247], off
	global_load_dwordx4 v[216:219], v[248:249], off
	global_load_dwordx4 v[220:223], v[250:251], off
	global_load_dwordx4 v[224:227], v[252:253], off
	global_load_dwordx4 v[228:231], v[254:255], off
	global_load_dwordx4 v[232:235], v[236:237], off
	v_lshl_add_u64 v[240:241], v[240:241], 0, s[6:7]
	v_lshl_add_u64 v[242:243], v[242:243], 0, s[6:7]
	v_lshl_add_u64 v[244:245], v[244:245], 0, s[6:7]
	v_lshl_add_u64 v[246:247], v[246:247], 0, s[6:7]
	v_lshl_add_u64 v[248:249], v[248:249], 0, s[6:7]
	v_lshl_add_u64 v[250:251], v[250:251], 0, s[6:7]
	v_lshl_add_u64 v[252:253], v[252:253], 0, s[6:7]
	v_lshl_add_u64 v[254:255], v[254:255], 0, s[6:7]
	v_lshl_add_u64 v[236:237], v[236:237], 0, s[6:7]
	s_barrier
	s_waitcnt vmcnt(17)
	v_mov_b64_e32 v[100:101], v[64:65]
	v_mov_b64_e32 v[96:97], v[48:49]
	v_mov_b64_e32 v[52:53], v[32:33]
	v_mov_b64_e32 v[44:45], v[24:25]
	v_mov_b64_e32 v[98:99], v[62:63]
	v_mov_b64_e32 v[94:95], v[46:47]
	v_mov_b64_e32 v[50:51], v[30:31]
	v_mov_b64_e32 v[42:43], v[22:23]
	ds_read_b128 v[46:49], v129
	ds_read_b128 v[54:57], v129 offset:64
	ds_read_b128 v[62:65], v129 offset:8448
	ds_read_b128 v[66:69], v129 offset:8512
	ds_read_b128 v[70:73], v129 offset:128
	ds_read_b128 v[22:25], v129 offset:192
	ds_read_b128 v[74:77], v129 offset:8576
	ds_read_b128 v[30:33], v129 offset:8640
	ds_read_b128 v[18:21], v129 offset:256
	ds_read_b128 v[58:61], v129 offset:320
	ds_read_b128 v[26:29], v129 offset:8704
	ds_read_b128 v[118:121], v129 offset:8768
	ds_read_b128 v[110:113], v129 offset:384
	ds_read_b128 v[106:109], v129 offset:448
	ds_read_b128 v[114:117], v129 offset:8832
	ds_read_b128 v[102:105], v129 offset:8896
	s_waitcnt lgkmcnt(14)
	v_mfma_f32_16x16x32_bf16 v[46:49], v[90:93], v[46:49], 0
	ds_read_b128 v[156:159], v146
	ds_read_b128 v[160:163], v147
	v_mov_b32_e32 v123, v122
	v_lshl_add_u64 v[34:35], s[78:79], 0, v[138:139]
	s_waitcnt lgkmcnt(14)
	v_mfma_f32_16x16x32_bf16 v[62:65], v[90:93], v[62:65], 0
	ds_read_b128 v[90:93], v146 offset:64
	ds_read_b128 v[164:167], v146 offset:4352
	ds_read_b128 v[168:171], v146 offset:4416
	v_pk_mul_f32 v[6:7], v[126:127], v[6:7]
	v_pk_mul_f32 v[2:3], v[126:127], v[2:3]
	v_mfma_f32_16x16x32_bf16 v[46:49], v[86:89], v[54:57], v[46:49]
	ds_read_b128 v[54:57], v147 offset:64
	ds_read_b128 v[172:175], v147 offset:4352
	ds_read_b128 v[176:179], v147 offset:4416
	v_pk_mul_f32 v[8:9], v[122:123], v[8:9]
	v_pk_mul_f32 v[4:5], v[122:123], v[4:5]
	v_pk_mul_f32 v[10:11], v[126:127], v[10:11]
	s_waitcnt lgkmcnt(4)
	v_mfma_f32_16x16x32_bf16 v[6:9], v[164:167], v[160:163], v[6:9]
	v_mul_f32_e64 v12, v122, v12
	v_mul_f32_e64 v13, v123, v13
	v_pk_mul_f32 v[14:15], v[126:127], v[14:15]
	v_pk_mul_f32 v[16:17], v[122:123], v[16:17]
	s_waitcnt lgkmcnt(1)
	v_mfma_f32_16x16x32_bf16 v[2:5], v[164:167], v[172:175], v[2:5]
	v_add_co_u32_e32 v164, vcc, s11, v34
	v_lshl_add_u64 v[40:41], s[78:79], 0, v[136:137]
	s_nop 0
	v_addc_co_u32_e32 v165, vcc, 0, v35, vcc
	v_add_co_u32_e32 v166, vcc, s12, v34
	v_mfma_f32_16x16x32_bf16 v[10:13], v[156:159], v[172:175], v[10:13]
	s_nop 0
	v_addc_co_u32_e32 v167, vcc, 0, v35, vcc
	v_add_co_u32_e32 v172, vcc, s13, v34
	v_mfma_f32_16x16x32_bf16 v[6:9], v[168:171], v[54:57], v[6:9]
	s_nop 0
	v_addc_co_u32_e32 v173, vcc, 0, v35, vcc
	v_add_co_u32_e32 v174, vcc, s16, v34
	s_waitcnt lgkmcnt(0)
	v_mfma_f32_16x16x32_bf16 v[2:5], v[168:171], v[176:179], v[2:5]
	v_addc_co_u32_e32 v175, vcc, 0, v35, vcc
	v_add_co_u32_e32 v168, vcc, s17, v34
	v_mfma_f32_16x16x32_bf16 v[14:17], v[156:159], v[160:163], v[14:17]
	s_nop 0
	v_addc_co_u32_e32 v169, vcc, 0, v35, vcc
	v_add_co_u32_e32 v170, vcc, s18, v34
	v_mfma_f32_16x16x32_bf16 v[62:65], v[86:89], v[66:69], v[62:65]
	s_nop 0
	v_addc_co_u32_e32 v171, vcc, 0, v35, vcc
	ds_read_b128 v[66:69], v146 offset:128
	ds_read_b128 v[180:183], v146 offset:192
	v_mfma_f32_16x16x32_bf16 v[46:49], v[82:85], v[70:73], v[46:49]
	ds_read_b128 v[184:187], v146 offset:4480
	ds_read_b128 v[188:191], v146 offset:4544
	ds_read_b128 v[156:159], v147 offset:128
	ds_read_b128 v[192:195], v147 offset:192
	ds_read_b128 v[160:163], v147 offset:4480
	ds_read_b128 v[196:199], v147 offset:4544
	v_mfma_f32_16x16x32_bf16 v[10:13], v[90:93], v[176:179], v[10:13]
	v_add_co_u32_e32 v176, vcc, s19, v34
	v_lshl_add_u64 v[38:39], s[78:79], 0, v[140:141]
	s_nop 0
	v_addc_co_u32_e32 v177, vcc, 0, v35, vcc
	v_mfma_f32_16x16x32_bf16 v[14:17], v[90:93], v[54:57], v[14:17]
	v_add_co_u32_e32 v178, vcc, s20, v34
	v_lshl_add_u64 v[36:37], s[78:79], 0, v[142:143]
	v_mfma_f32_16x16x32_bf16 v[62:65], v[82:85], v[74:77], v[62:65]
	v_addc_co_u32_e32 v179, vcc, 0, v35, vcc
	global_load_dwordx4 v[90:93], v[36:37], off offset:-256
	global_load_dwordx4 v[86:89], v[36:37], off offset:-192
	v_mfma_f32_16x16x32_bf16 v[54:57], v[78:81], v[22:25], v[46:49]
	s_add_i32 s10, s10, -1
	v_lshl_add_u64 v[136:137], v[136:137], 0, s[0:1]
	v_lshl_add_u64 v[140:141], v[140:141], 0, s[6:7]
	s_waitcnt lgkmcnt(1)
	v_mfma_f32_16x16x32_bf16 v[10:13], v[66:69], v[160:163], v[10:13]
	v_lshl_add_u64 v[138:139], v[138:139], 0, s[6:7]
	v_lshl_add_u64 v[142:143], v[142:143], 0, s[8:9]
	s_cmp_lg_u32 s10, 0
	v_mfma_f32_16x16x32_bf16 v[2:5], v[184:187], v[160:163], v[2:5]
	v_add_co_u32_e32 v160, vcc, s22, v40
	v_add_u32_e32 v135, 0x2000, v131
	s_nop 0
	v_addc_co_u32_e32 v161, vcc, 0, v41, vcc
	v_mfma_f32_16x16x32_bf16 v[14:17], v[66:69], v[156:159], v[14:17]
	v_add_co_u32_e32 v162, vcc, s23, v40
	v_mfma_f32_16x16x32_bf16 v[74:77], v[78:81], v[30:33], v[62:65]
	s_nop 0
	v_addc_co_u32_e32 v163, vcc, 0, v41, vcc
	global_load_dwordx4 v[82:85], v[36:37], off offset:-128
	global_load_dwordx4 v[78:81], v[36:37], off offset:-64
	global_load_dwordx4 v[62:65], v[36:37], off
	v_mfma_f32_16x16x32_bf16 v[66:69], v[98:101], v[18:21], v[54:57]
	global_load_dwordx4 v[46:49], v[36:37], off offset:64
	global_load_dwordx4 v[30:33], v[36:37], off offset:128
	global_load_dwordx4 v[22:25], v[36:37], off offset:192
	v_mfma_f32_16x16x32_bf16 v[6:9], v[184:187], v[156:159], v[6:9]
	v_add_co_u32_e32 v184, vcc, s24, v40
	s_nop 1
	v_addc_co_u32_e32 v185, vcc, 0, v41, vcc
	v_mfma_f32_16x16x32_bf16 v[14:17], v[180:183], v[192:195], v[14:17]
	s_waitcnt lgkmcnt(0)
	v_mfma_f32_16x16x32_bf16 v[10:13], v[180:183], v[196:199], v[10:13]
	v_add_co_u32_e32 v180, vcc, s25, v40
	v_mfma_f32_16x16x32_bf16 v[98:101], v[98:101], v[26:29], v[74:77]
	s_nop 0
	v_addc_co_u32_e32 v181, vcc, 0, v41, vcc
	v_mfma_f32_16x16x32_bf16 v[156:159], v[94:97], v[58:61], v[66:69]
	s_nop 1
	v_mfma_f32_16x16x32_bf16 v[6:9], v[188:191], v[192:195], v[6:9]
	v_mfma_f32_16x16x32_bf16 v[2:5], v[188:191], v[196:199], v[2:5]
	v_mfma_f32_16x16x32_bf16 v[94:97], v[94:97], v[118:121], v[98:101]
	v_bfe_u32 v118, v10, 16, 1
	v_bfe_u32 v120, v12, 16, 1
	v_bfe_u32 v119, v11, 16, 1
	v_bfe_u32 v98, v14, 16, 1
	v_bfe_u32 v99, v15, 16, 1
	v_bfe_u32 v100, v16, 16, 1
	v_bfe_u32 v101, v17, 16, 1
	v_bfe_u32 v121, v13, 16, 1
	v_bfe_u32 v155, v6, 16, 1
	v_bfe_u32 v164, v7, 16, 1
	v_bfe_u32 v165, v8, 16, 1
	v_bfe_u32 v166, v9, 16, 1
	v_bfe_u32 v167, v2, 16, 1
	v_bfe_u32 v168, v3, 16, 1
	v_bfe_u32 v169, v4, 16, 1
	v_bfe_u32 v170, v5, 16, 1
	v_add3_u32 v98, v14, v98, s21
	v_add3_u32 v171, v15, v99, s21
	v_add3_u32 v99, v16, v100, s21
	v_add3_u32 v172, v17, v101, s21
	v_add3_u32 v100, v10, v118, s21
	v_add3_u32 v101, v12, v120, s21
	v_add3_u32 v118, v11, v119, s21
	v_add3_u32 v119, v13, v121, s21
	v_add3_u32 v120, v6, v155, s21
	v_add3_u32 v121, v7, v164, s21
	v_add3_u32 v155, v8, v165, s21
	v_add3_u32 v164, v9, v166, s21
	v_add3_u32 v165, v2, v167, s21
	v_add3_u32 v166, v3, v168, s21
	v_add3_u32 v167, v4, v169, s21
	v_add3_u32 v168, v5, v170, s21
	v_lshrrev_b32_e32 v169, 16, v98
	v_lshrrev_b32_e32 v170, 16, v99
	v_lshrrev_b32_e32 v173, 16, v100
	v_lshrrev_b32_e32 v174, 16, v101
	v_mfma_f32_16x16x32_bf16 v[98:101], v[50:53], v[110:113], v[156:159]
	v_lshrrev_b32_e32 v120, 16, v120
	v_lshrrev_b32_e32 v155, 16, v155
	v_lshrrev_b32_e32 v165, 16, v165
	v_mfma_f32_16x16x32_bf16 v[50:53], v[50:53], v[114:117], v[94:97]
	v_lshrrev_b32_e32 v156, 16, v167
	v_and_or_b32 v110, v171, s26, v169
	v_and_or_b32 v111, v172, s26, v170
	v_mfma_f32_16x16x32_bf16 v[94:97], v[42:45], v[106:109], v[98:101]
	v_and_or_b32 v114, v121, s26, v120
	v_and_or_b32 v115, v164, s26, v155
	v_and_or_b32 v112, v118, s26, v173
	v_mfma_f32_16x16x32_bf16 v[42:45], v[42:45], v[102:105], v[50:53]
	v_and_or_b32 v113, v119, s26, v174
	v_and_or_b32 v98, v166, s26, v165
	v_and_or_b32 v99, v168, s26, v156
	s_nop 0
	v_mul_f32_e32 v50, v148, v94
	v_mul_f32_e32 v51, v145, v95
	s_nop 1
	v_mul_f32_e32 v42, v148, v42
	v_mul_f32_e32 v43, v145, v43
	v_mul_f32_e32 v52, v144, v96
	v_mul_f32_e32 v44, v144, v44
	v_mul_f32_e32 v53, v1, v97
	v_mul_f32_e32 v45, v1, v45
	v_bfe_u32 v94, v50, 16, 1
	v_bfe_u32 v95, v42, 16, 1
	v_bfe_u32 v96, v51, 16, 1
	v_bfe_u32 v97, v43, 16, 1
	v_bfe_u32 v100, v52, 16, 1
	v_bfe_u32 v101, v44, 16, 1
	v_bfe_u32 v102, v53, 16, 1
	v_bfe_u32 v103, v45, 16, 1
	v_add3_u32 v50, v50, v94, s21
	v_add3_u32 v42, v42, v95, s21
	v_add3_u32 v51, v51, v96, s21
	v_add3_u32 v43, v43, v97, s21
	v_add3_u32 v52, v52, v100, s21
	v_add3_u32 v44, v44, v101, s21
	v_add3_u32 v53, v53, v102, s21
	v_add3_u32 v45, v45, v103, s21
	global_store_short_d16_hi v[160:161], v50, off offset:2048
	global_store_short_d16_hi v[160:161], v42, off offset:2080
	global_store_short_d16_hi v[162:163], v51, off offset:2048
	global_store_short_d16_hi v[162:163], v43, off offset:2080
	global_store_short_d16_hi v[184:185], v52, off offset:2048
	global_store_short_d16_hi v[184:185], v44, off offset:2080
	global_store_short_d16_hi v[180:181], v53, off offset:2048
	global_store_short_d16_hi v[180:181], v45, off offset:2080
	s_barrier
	ds_write2_b64 v131, v[110:111], v[114:115] offset1:4
	ds_write2_b64 v135, v[112:113], v[98:99] offset0:32 offset1:36
	s_cbranch_scc1 .LBB0_639
	s_waitcnt vmcnt(16)
	ds_write_b128 v125, v[200:203]
	ds_write_b128 v133, v[204:207]
	ds_write_b128 v125, v[208:211] offset:17408
	ds_write_b128 v149, v[212:215]
	ds_write_b128 v125, v[216:219] offset:34816
	ds_write_b128 v150, v[220:223]
	ds_write_b128 v125, v[224:227] offset:52224
	s_waitcnt vmcnt(8)
	ds_write_b128 v151, v[228:231]
	ds_write_b128 v154, v[232:235]
	s_waitcnt lgkmcnt(0)
	s_barrier
	ds_read_b128 v[18:21], v129
	ds_read_b128 v[26:29], v129 offset:64
	ds_read_b128 v[34:37], v129 offset:8448
	ds_read_b128 v[38:41], v129 offset:8512
	s_waitcnt lgkmcnt(3)
	v_mfma_f32_16x16x32_bf16 v[18:21], v[90:93], v[18:21], 0
	s_lshl_b32 s0, s15, 1
	s_add_u32 s0, s78, s0
	s_addc_u32 s1, s79, 0
	s_waitcnt lgkmcnt(1)
	v_mfma_f32_16x16x32_bf16 v[34:37], v[90:93], v[34:37], 0
	s_lshl_b32 s6, s14, 1
	s_add_u32 s0, s0, s6
	v_mov_b32_e32 v51, 0
	v_mfma_f32_16x16x32_bf16 v[18:21], v[86:89], v[26:29], v[18:21]
	s_addc_u32 s1, s1, 0
	v_lshlrev_b32_e32 v50, 1, v130
	v_mov_b32_e32 v135, v51
	s_waitcnt lgkmcnt(0)
	v_mfma_f32_16x16x32_bf16 v[26:29], v[86:89], v[38:41], v[34:37]
	s_nop 2
	ds_read_b128 v[34:37], v129 offset:128
	ds_read_b128 v[38:41], v129 offset:192
	s_or_b32 s4, s4, 0x3f80
	v_lshl_add_u64 v[52:53], s[0:1], 0, v[50:51]
	s_waitcnt lgkmcnt(1)
	v_mfma_f32_16x16x32_bf16 v[18:21], v[82:85], v[34:37], v[18:21]
	ds_read_b128 v[34:37], v129 offset:8576
	ds_read_b128 v[42:45], v129 offset:8640
	s_mov_b64 s[0:1], 0xf000800
	v_lshl_add_u64 v[54:55], v[52:53], 0, s[0:1]
	s_waitcnt lgkmcnt(1)
	v_mfma_f32_16x16x32_bf16 v[26:29], v[82:85], v[34:37], v[26:29]
	ds_read_b128 v[34:37], v129 offset:256
	s_movk_i32 s0, 0x7fff
	v_mov_b32_e32 v133, v51
	v_mfma_f32_16x16x32_bf16 v[18:21], v[78:81], v[38:41], v[18:21]
	v_mul_f32_e64 v16, v122, v16
	v_mul_f32_e64 v17, v123, v17
	v_pk_mul_f32 v[14:15], v[126:127], v[14:15]
	v_pk_mul_f32 v[8:9], v[122:123], v[8:9]
	s_waitcnt lgkmcnt(1)
	v_mfma_f32_16x16x32_bf16 v[26:29], v[78:81], v[42:45], v[26:29]
	ds_read_b128 v[38:41], v129 offset:8704
	ds_read_b128 v[42:45], v129 offset:320
	v_pk_mul_f32 v[6:7], v[126:127], v[6:7]
	v_pk_mul_f32 v[12:13], v[122:123], v[12:13]
	s_waitcnt lgkmcnt(2)
	v_mfma_f32_16x16x32_bf16 v[18:21], v[62:65], v[34:37], v[18:21]
	ds_read_b128 v[34:37], v129 offset:8768
	v_pk_mul_f32 v[10:11], v[126:127], v[10:11]
	v_mov_b32_e32 v125, v51
	s_waitcnt lgkmcnt(2)
	v_mfma_f32_16x16x32_bf16 v[26:29], v[62:65], v[38:41], v[26:29]
	ds_read_b128 v[38:41], v129 offset:384
	v_pk_mul_f32 v[4:5], v[122:123], v[4:5]
	v_pk_mul_f32 v[2:3], v[126:127], v[2:3]
	s_waitcnt lgkmcnt(2)
	v_mfma_f32_16x16x32_bf16 v[18:21], v[46:49], v[42:45], v[18:21]
	s_mov_b32 s1, 0xffff0000
	s_waitcnt lgkmcnt(1)
	v_mfma_f32_16x16x32_bf16 v[26:29], v[46:49], v[34:37], v[26:29]
	ds_read_b128 v[34:37], v129 offset:8832
	ds_read_b128 v[42:45], v129 offset:448
	s_waitcnt lgkmcnt(2)
	v_mfma_f32_16x16x32_bf16 v[18:21], v[30:33], v[38:41], v[18:21]
	ds_read_b128 v[38:41], v129 offset:8896
	v_mov_b32_e32 v129, v51
	s_waitcnt lgkmcnt(2)
	v_mfma_f32_16x16x32_bf16 v[26:29], v[30:33], v[34:37], v[26:29]
	v_lshl_add_u64 v[30:31], s[4:5], 0, v[134:135]
	v_lshlrev_b64 v[30:31], 12, v[30:31]
	s_waitcnt lgkmcnt(1)
	v_mfma_f32_16x16x32_bf16 v[18:21], v[22:25], v[42:45], v[18:21]
	s_waitcnt lgkmcnt(0)
	v_mfma_f32_16x16x32_bf16 v[22:25], v[22:25], v[38:41], v[26:29]
	s_nop 2
	v_lshl_add_u64 v[26:27], v[54:55], 0, v[30:31]
	s_nop 1
	v_mul_f32_e32 v18, v148, v18
	v_bfe_u32 v28, v18, 16, 1
	v_add3_u32 v18, v18, v28, s0
	global_store_short_d16_hi v[26:27], v18, off
	v_mul_f32_e32 v18, v148, v22
	v_bfe_u32 v22, v18, 16, 1
	v_add3_u32 v18, v18, v22, s0
	global_store_short_d16_hi v[26:27], v18, off offset:32
	ds_read_b128 v[26:29], v146
	v_lshl_add_u64 v[30:31], s[4:5], 0, v[132:133]
	v_lshlrev_b64 v[56:57], 12, v[30:31]
	ds_read_b128 v[30:33], v147
	ds_read_b128 v[34:37], v146 offset:4352
	ds_read_b128 v[38:41], v147 offset:4352
	ds_read_b128 v[42:45], v146 offset:64
	ds_read_b128 v[46:49], v147 offset:64
	v_mul_f32_e32 v18, v145, v19
	v_bfe_u32 v19, v18, 16, 1
	s_waitcnt lgkmcnt(4)
	v_mfma_f32_16x16x32_bf16 v[14:17], v[26:29], v[30:33], v[14:17]
	v_add3_u32 v18, v18, v19, s0
	ds_read_b128 v[50:53], v147 offset:4416
	v_mul_f32_e32 v20, v144, v20
	s_waitcnt lgkmcnt(4)
	v_mfma_f32_16x16x32_bf16 v[6:9], v[34:37], v[30:33], v[6:9]
	v_lshl_add_u64 v[30:31], v[54:55], 0, v[56:57]
	global_store_short_d16_hi v[30:31], v18, off
	v_mul_f32_e32 v18, v145, v23
	v_bfe_u32 v19, v18, 16, 1
	s_waitcnt lgkmcnt(3)
	v_mfma_f32_16x16x32_bf16 v[10:13], v[26:29], v[38:41], v[10:13]
	ds_read_b128 v[26:29], v146 offset:4416
	v_add3_u32 v18, v18, v19, s0
	global_store_short_d16_hi v[30:31], v18, off offset:32
	ds_read_b128 v[30:33], v146 offset:128
	v_mfma_f32_16x16x32_bf16 v[2:5], v[34:37], v[38:41], v[2:5]
	v_lshl_add_u64 v[18:19], s[4:5], 0, v[128:129]
	v_lshlrev_b64 v[18:19], 12, v[18:19]
	v_bfe_u32 v22, v20, 16, 1
	s_waitcnt lgkmcnt(3)
	v_mfma_f32_16x16x32_bf16 v[14:17], v[42:45], v[46:49], v[14:17]
	v_lshl_add_u64 v[18:19], v[54:55], 0, v[18:19]
	v_add3_u32 v20, v20, v22, s0
	s_waitcnt lgkmcnt(2)
	v_mfma_f32_16x16x32_bf16 v[10:13], v[42:45], v[50:53], v[10:13]
	s_waitcnt lgkmcnt(1)
	v_mfma_f32_16x16x32_bf16 v[6:9], v[26:29], v[46:49], v[6:9]
	v_mfma_f32_16x16x32_bf16 v[2:5], v[26:29], v[50:53], v[2:5]
	ds_read_b128 v[26:29], v147 offset:128
	ds_read_b128 v[34:37], v146 offset:4480
	ds_read_b128 v[38:41], v147 offset:4480
	ds_read_b128 v[42:45], v146 offset:192
	ds_read_b128 v[46:49], v147 offset:192
	global_store_short_d16_hi v[18:19], v20, off
	v_mul_f32_e32 v20, v144, v24
	s_waitcnt lgkmcnt(4)
	v_mfma_f32_16x16x32_bf16 v[14:17], v[30:33], v[26:29], v[14:17]
	v_bfe_u32 v22, v20, 16, 1
	v_add3_u32 v20, v20, v22, s0
	global_store_short_d16_hi v[18:19], v20, off offset:32
	v_lshl_add_u64 v[18:19], s[4:5], 0, v[124:125]
	v_mul_f32_e32 v20, v1, v21
	v_lshlrev_b64 v[18:19], 12, v[18:19]
	s_waitcnt lgkmcnt(0)
	v_mfma_f32_16x16x32_bf16 v[14:17], v[42:45], v[46:49], v[14:17]
	v_bfe_u32 v21, v20, 16, 1
	ds_read_b128 v[50:53], v147 offset:4544
	v_lshl_add_u64 v[18:19], v[54:55], 0, v[18:19]
	v_add3_u32 v20, v20, v21, s0
	v_mul_f32_e32 v1, v1, v25
	v_mfma_f32_16x16x32_bf16 v[10:13], v[30:33], v[38:41], v[10:13]
	global_store_short_d16_hi v[18:19], v20, off
	v_bfe_u32 v20, v1, 16, 1
	ds_read_b128 v[30:33], v146 offset:4544
	v_add3_u32 v1, v1, v20, s0
	global_store_short_d16_hi v[18:19], v1, off offset:32
	v_bfe_u32 v1, v14, 16, 1
	v_add3_u32 v1, v14, v1, s0
	v_bfe_u32 v14, v15, 16, 1
	s_waitcnt lgkmcnt(1)
	v_mfma_f32_16x16x32_bf16 v[10:13], v[42:45], v[50:53], v[10:13]
	v_lshrrev_b32_e32 v1, 16, v1
	v_add3_u32 v14, v15, v14, s0
	v_and_or_b32 v14, v14, s1, v1
	v_bfe_u32 v1, v16, 16, 1
	v_mfma_f32_16x16x32_bf16 v[6:9], v[34:37], v[26:29], v[6:9]
	v_add3_u32 v1, v16, v1, s0
	v_bfe_u32 v15, v17, 16, 1
	v_lshrrev_b32_e32 v1, 16, v1
	v_add3_u32 v15, v17, v15, s0
	v_and_or_b32 v15, v15, s1, v1
	v_bfe_u32 v1, v10, 16, 1
	v_add3_u32 v1, v10, v1, s0
	v_bfe_u32 v10, v11, 16, 1
	s_waitcnt lgkmcnt(0)
	v_mfma_f32_16x16x32_bf16 v[6:9], v[30:33], v[46:49], v[6:9]
	v_lshrrev_b32_e32 v1, 16, v1
	v_add3_u32 v10, v11, v10, s0
	v_and_or_b32 v10, v10, s1, v1
	v_bfe_u32 v1, v12, 16, 1
	v_mfma_f32_16x16x32_bf16 v[2:5], v[34:37], v[38:41], v[2:5]
	v_add3_u32 v1, v12, v1, s0
	v_bfe_u32 v11, v13, 16, 1
	v_lshrrev_b32_e32 v1, 16, v1
	v_add3_u32 v11, v13, v11, s0
	v_and_or_b32 v11, v11, s1, v1
	v_bfe_u32 v1, v6, 16, 1
	v_add3_u32 v1, v6, v1, s0
	v_bfe_u32 v6, v7, 16, 1
	v_mfma_f32_16x16x32_bf16 v[2:5], v[30:33], v[50:53], v[2:5]
	v_lshrrev_b32_e32 v1, 16, v1
	v_add3_u32 v6, v7, v6, s0
	v_and_or_b32 v6, v6, s1, v1
	v_bfe_u32 v1, v8, 16, 1
	v_add3_u32 v1, v8, v1, s0
	v_bfe_u32 v7, v9, 16, 1
	v_lshrrev_b32_e32 v1, 16, v1
	v_add3_u32 v7, v9, v7, s0
	v_and_or_b32 v7, v7, s1, v1
	v_bfe_u32 v1, v2, 16, 1
	v_add3_u32 v1, v2, v1, s0
	v_bfe_u32 v2, v3, 16, 1
	v_lshrrev_b32_e32 v1, 16, v1
	v_add3_u32 v2, v3, v2, s0
	v_and_or_b32 v2, v2, s1, v1
	v_bfe_u32 v1, v4, 16, 1
	v_add3_u32 v1, v4, v1, s0
	v_bfe_u32 v3, v5, 16, 1
	v_lshrrev_b32_e32 v1, 16, v1
	v_add3_u32 v3, v5, v3, s0
	v_and_or_b32 v3, v3, s1, v1
	v_add_u32_e32 v1, 0x2000, v131
	s_barrier
	ds_write2_b64 v131, v[14:15], v[6:7] offset1:4
	ds_write2_b64 v1, v[10:11], v[2:3] offset0:32 offset1:36
	s_waitcnt lgkmcnt(0)
	s_barrier

	.amdhsa_kernel _Z10fwd_kernel4Args
		.amdhsa_group_segment_fixed_size 0
		.amdhsa_private_segment_fixed_size 0
		.amdhsa_kernarg_size 464
		.amdhsa_user_sgpr_count 2
		.amdhsa_user_sgpr_dispatch_ptr 0
		.amdhsa_user_sgpr_queue_ptr 0
		.amdhsa_user_sgpr_kernarg_segment_ptr 1
		.amdhsa_user_sgpr_dispatch_id 0
		.amdhsa_user_sgpr_kernarg_preload_length 0
		.amdhsa_user_sgpr_kernarg_preload_offset 0
		.amdhsa_user_sgpr_private_segment_size 0
		.amdhsa_uses_dynamic_stack 0
		.amdhsa_enable_private_segment 0
		.amdhsa_system_sgpr_workgroup_id_x 1
		.amdhsa_system_sgpr_workgroup_id_y 0
		.amdhsa_system_sgpr_workgroup_id_z 0
		.amdhsa_system_sgpr_workgroup_info 0
		.amdhsa_system_vgpr_workitem_id 2
		.amdhsa_next_free_vgpr 256
		.amdhsa_next_free_sgpr 98
		.amdhsa_accum_offset 256
		.amdhsa_reserve_vcc 1
		.amdhsa_float_round_mode_32 0
		.amdhsa_float_round_mode_16_64 0
		.amdhsa_float_denorm_mode_32 3
		.amdhsa_float_denorm_mode_16_64 3
		.amdhsa_dx10_clamp 1
		.amdhsa_ieee_mode 1
		.amdhsa_fp16_overflow 0
		.amdhsa_tg_split 0
		.amdhsa_exception_fp_ieee_invalid_op 0
		.amdhsa_exception_fp_denorm_src 0
		.amdhsa_exception_fp_ieee_div_zero 0
		.amdhsa_exception_fp_ieee_overflow 0
		.amdhsa_exception_fp_ieee_underflow 0
		.amdhsa_exception_fp_ieee_inexact 0
		.amdhsa_exception_int_div_zero 0
	.end_amdhsa_kernel

amdhsa.kernels:
  - .agpr_count:     0
    .args:
      - .offset:         0
        .size:           208
        .value_kind:     by_value
      - .offset:         208
        .size:           4
        .value_kind:     hidden_block_count_x
      - .offset:         212
        .size:           4
        .value_kind:     hidden_block_count_y
      - .offset:         216
        .size:           4
        .value_kind:     hidden_block_count_z
      - .offset:         220
        .size:           2
        .value_kind:     hidden_group_size_x
      - .offset:         222
        .size:           2
        .value_kind:     hidden_group_size_y
      - .offset:         224
        .size:           2
        .value_kind:     hidden_group_size_z
      - .offset:         226
        .size:           2
        .value_kind:     hidden_remainder_x
      - .offset:         228
        .size:           2
        .value_kind:     hidden_remainder_y
      - .offset:         230
        .size:           2
        .value_kind:     hidden_remainder_z
      - .offset:         248
        .size:           8
        .value_kind:     hidden_global_offset_x
      - .offset:         256
        .size:           8
        .value_kind:     hidden_global_offset_y
      - .offset:         264
        .size:           8
        .value_kind:     hidden_global_offset_z
      - .offset:         272
        .size:           2
        .value_kind:     hidden_grid_dims
      - .offset:         296
        .size:           8
        .value_kind:     hidden_multigrid_sync_arg
      - .offset:         328
        .size:           4
        .value_kind:     hidden_dynamic_lds_size
    .group_segment_fixed_size: 0
    .kernarg_segment_align: 8
    .kernarg_segment_size: 464
    .language:       OpenCL C
    .language_version:
      - 2
      - 0
    .max_flat_workgroup_size: 512
    .name:           _Z10fwd_kernel4Args
    .private_segment_fixed_size: 0
    .sgpr_count:     104
    .sgpr_spill_count: 76
    .symbol:         _Z10fwd_kernel4Args.kd
    .uniform_work_group_size: 1
    .uses_dynamic_stack: false
    .vgpr_count:     256
    .vgpr_spill_count: 0
    .wavefront_size: 64
